# UP epilogue: redundant canonicalising v_max removed in front of max(0,x) (bit-exact), store-data wait states kept with s_nop
# baseline (speedup 1.0000x reference)
.LBB0_292:
	v_lshl_add_u32 v144, s33, 8, v140
	v_lshl_or_b32 v138, s21, 8, v142
	v_ashrrev_i32_e32 v145, 31, v144
	v_ashrrev_i32_e32 v139, 31, v138
	v_lshlrev_b64 v[146:147], 13, v[144:145]
	v_lshl_add_u64 v[146:147], s[46:47], 0, v[146:147]
	v_lshlrev_b64 v[148:149], 1, v[138:139]
	v_max_f32_e32 v120, 0, v120
	v_max_f32_e32 v121, 0, v121
	v_lshl_add_u64 v[138:139], v[146:147], 0, v[148:149]
	v_pk_mul_f32 v[146:147], v[120:121], v[120:121]
	v_max_f32_e32 v122, 0, v122
	v_max_f32_e32 v124, 0, v124
	v_max_f32_e32 v125, 0, v125
	v_max_f32_e32 v120, 0, v126
	v_max_f32_e32 v121, 0, v127
	v_max_f32_e32 v123, 0, v123
	v_pk_mul_f32 v[124:125], v[124:125], v[124:125]
	v_pk_mul_f32 v[126:127], v[120:121], v[120:121]
	v_pk_mul_f32 v[150:151], v[122:123], v[122:123]
	v_cvt_pk_bf16_f32 v120, v124, v125
	v_cvt_pk_bf16_f32 v121, v126, v127
	v_cvt_pk_bf16_f32 v122, v146, v147
	v_cvt_pk_bf16_f32 v123, v150, v151
	v_max_f32_e32 v112, 0, v112
	v_max_f32_e32 v113, 0, v113
	global_store_dwordx4 v[138:139], v[120:123], off
	s_nop 1
	v_pk_mul_f32 v[120:121], v[112:113], v[112:113]
	v_max_f32_e32 v114, 0, v114
	v_max_f32_e32 v116, 0, v116
	v_max_f32_e32 v117, 0, v117
	v_max_f32_e32 v112, 0, v118
	v_max_f32_e32 v113, 0, v119
	v_max_f32_e32 v115, 0, v115
	v_pk_mul_f32 v[116:117], v[116:117], v[116:117]
	v_pk_mul_f32 v[118:119], v[112:113], v[112:113]
	v_pk_mul_f32 v[122:123], v[114:115], v[114:115]
	v_cvt_pk_bf16_f32 v112, v116, v117
	v_cvt_pk_bf16_f32 v113, v118, v119
	v_cvt_pk_bf16_f32 v114, v120, v121
	v_cvt_pk_bf16_f32 v115, v122, v123
	v_max_f32_e32 v104, 0, v104
	v_max_f32_e32 v105, 0, v105
	global_store_dwordx4 v[138:139], v[112:115], off offset:256
	s_nop 1
	v_or_b32_e32 v112, 16, v144
	v_pk_mul_f32 v[114:115], v[104:105], v[104:105]
	v_ashrrev_i32_e32 v113, 31, v112
	v_max_f32_e32 v106, 0, v106
	v_lshlrev_b64 v[112:113], 13, v[112:113]
	v_max_f32_e32 v108, 0, v108
	v_max_f32_e32 v109, 0, v109
	v_max_f32_e32 v104, 0, v110
	v_max_f32_e32 v105, 0, v111
	v_max_f32_e32 v107, 0, v107
	v_lshl_add_u64 v[112:113], s[46:47], 0, v[112:113]
	v_pk_mul_f32 v[108:109], v[108:109], v[108:109]
	v_pk_mul_f32 v[110:111], v[104:105], v[104:105]
	v_pk_mul_f32 v[116:117], v[106:107], v[106:107]
	v_lshl_add_u64 v[112:113], v[112:113], 0, v[148:149]
	v_cvt_pk_bf16_f32 v104, v108, v109
	v_cvt_pk_bf16_f32 v105, v110, v111
	v_cvt_pk_bf16_f32 v106, v114, v115
	v_cvt_pk_bf16_f32 v107, v116, v117
	v_max_f32_e32 v96, 0, v96
	v_max_f32_e32 v97, 0, v97
	global_store_dwordx4 v[112:113], v[104:107], off
	s_nop 1
	v_pk_mul_f32 v[104:105], v[96:97], v[96:97]
	v_max_f32_e32 v98, 0, v98
	v_max_f32_e32 v100, 0, v100
	v_max_f32_e32 v101, 0, v101
	v_max_f32_e32 v96, 0, v102
	v_max_f32_e32 v97, 0, v103
	v_max_f32_e32 v99, 0, v99
	v_pk_mul_f32 v[100:101], v[100:101], v[100:101]
	v_pk_mul_f32 v[102:103], v[96:97], v[96:97]
	v_pk_mul_f32 v[106:107], v[98:99], v[98:99]
	v_cvt_pk_bf16_f32 v96, v100, v101
	v_cvt_pk_bf16_f32 v97, v102, v103
	v_cvt_pk_bf16_f32 v98, v104, v105
	v_cvt_pk_bf16_f32 v99, v106, v107
	v_max_f32_e32 v88, 0, v88
	v_max_f32_e32 v89, 0, v89
	global_store_dwordx4 v[112:113], v[96:99], off offset:256
	s_nop 1
	v_or_b32_e32 v96, 32, v144
	v_pk_mul_f32 v[98:99], v[88:89], v[88:89]
	v_ashrrev_i32_e32 v97, 31, v96
	v_max_f32_e32 v90, 0, v90
	v_lshlrev_b64 v[96:97], 13, v[96:97]
	v_max_f32_e32 v92, 0, v92
	v_max_f32_e32 v93, 0, v93
	v_max_f32_e32 v88, 0, v94
	v_max_f32_e32 v89, 0, v95
	v_max_f32_e32 v91, 0, v91
	v_lshl_add_u64 v[96:97], s[46:47], 0, v[96:97]
	v_pk_mul_f32 v[92:93], v[92:93], v[92:93]
	v_pk_mul_f32 v[94:95], v[88:89], v[88:89]
	v_pk_mul_f32 v[100:101], v[90:91], v[90:91]
	v_lshl_add_u64 v[96:97], v[96:97], 0, v[148:149]
	v_cvt_pk_bf16_f32 v88, v92, v93
	v_cvt_pk_bf16_f32 v89, v94, v95
	v_cvt_pk_bf16_f32 v90, v98, v99
	v_cvt_pk_bf16_f32 v91, v100, v101
	v_max_f32_e32 v80, 0, v80
	v_max_f32_e32 v81, 0, v81
	global_store_dwordx4 v[96:97], v[88:91], off
	s_nop 1
	v_pk_mul_f32 v[88:89], v[80:81], v[80:81]
	v_max_f32_e32 v82, 0, v82
	v_max_f32_e32 v84, 0, v84
	v_max_f32_e32 v85, 0, v85
	v_max_f32_e32 v80, 0, v86
	v_max_f32_e32 v81, 0, v87
	v_max_f32_e32 v83, 0, v83
	v_pk_mul_f32 v[84:85], v[84:85], v[84:85]
	v_pk_mul_f32 v[86:87], v[80:81], v[80:81]
	v_pk_mul_f32 v[90:91], v[82:83], v[82:83]
	v_cvt_pk_bf16_f32 v80, v84, v85
	v_cvt_pk_bf16_f32 v81, v86, v87
	v_cvt_pk_bf16_f32 v82, v88, v89
	v_cvt_pk_bf16_f32 v83, v90, v91
	v_max_f32_e32 v72, 0, v72
	v_max_f32_e32 v73, 0, v73
	global_store_dwordx4 v[96:97], v[80:83], off offset:256
	s_nop 1
	v_or_b32_e32 v80, 48, v144
	v_pk_mul_f32 v[82:83], v[72:73], v[72:73]
	v_ashrrev_i32_e32 v81, 31, v80
	v_max_f32_e32 v74, 0, v74
	v_lshlrev_b64 v[80:81], 13, v[80:81]
	v_max_f32_e32 v76, 0, v76
	v_max_f32_e32 v77, 0, v77
	v_max_f32_e32 v72, 0, v78
	v_max_f32_e32 v73, 0, v79
	v_max_f32_e32 v75, 0, v75
	v_lshl_add_u64 v[80:81], s[46:47], 0, v[80:81]
	v_pk_mul_f32 v[76:77], v[76:77], v[76:77]
	v_pk_mul_f32 v[78:79], v[72:73], v[72:73]
	v_pk_mul_f32 v[84:85], v[74:75], v[74:75]
	v_lshl_add_u64 v[80:81], v[80:81], 0, v[148:149]
	v_cvt_pk_bf16_f32 v72, v76, v77
	v_cvt_pk_bf16_f32 v73, v78, v79
	v_cvt_pk_bf16_f32 v74, v82, v83
	v_cvt_pk_bf16_f32 v75, v84, v85
	v_max_f32_e32 v64, 0, v64
	v_max_f32_e32 v65, 0, v65
	global_store_dwordx4 v[80:81], v[72:75], off
	s_nop 1
	v_pk_mul_f32 v[72:73], v[64:65], v[64:65]
	v_max_f32_e32 v66, 0, v66
	v_max_f32_e32 v68, 0, v68
	v_max_f32_e32 v69, 0, v69
	v_max_f32_e32 v64, 0, v70
	v_max_f32_e32 v65, 0, v71
	v_max_f32_e32 v67, 0, v67
	v_pk_mul_f32 v[68:69], v[68:69], v[68:69]
	v_pk_mul_f32 v[70:71], v[64:65], v[64:65]
	v_pk_mul_f32 v[74:75], v[66:67], v[66:67]
	v_cvt_pk_bf16_f32 v64, v68, v69
	v_cvt_pk_bf16_f32 v65, v70, v71
	v_cvt_pk_bf16_f32 v66, v72, v73
	v_cvt_pk_bf16_f32 v67, v74, v75
	v_max_f32_e32 v56, 0, v56
	v_max_f32_e32 v57, 0, v57
	global_store_dwordx4 v[80:81], v[64:67], off offset:256
	s_nop 1
	v_pk_mul_f32 v[66:67], v[56:57], v[56:57]
	s_mov_b64 s[4:5], 0x100000
	v_max_f32_e32 v60, 0, v60
	v_max_f32_e32 v61, 0, v61
	v_max_f32_e32 v58, 0, v58
	v_lshl_add_u64 v[64:65], v[138:139], 0, s[4:5]
	v_pk_mul_f32 v[60:61], v[60:61], v[60:61]
	v_max_f32_e32 v56, 0, v62
	v_max_f32_e32 v57, 0, v63
	v_max_f32_e32 v59, 0, v59
	s_mov_b32 s4, 0x100000
	v_pk_mul_f32 v[62:63], v[56:57], v[56:57]
	v_pk_mul_f32 v[68:69], v[58:59], v[58:59]
	v_cvt_pk_bf16_f32 v56, v60, v61
	v_add_co_u32_e32 v60, vcc, s4, v138
	v_cvt_pk_bf16_f32 v57, v62, v63
	v_cvt_pk_bf16_f32 v58, v66, v67
	v_cvt_pk_bf16_f32 v59, v68, v69
	v_addc_co_u32_e32 v61, vcc, 0, v139, vcc
	v_max_f32_e32 v48, 0, v48
	v_max_f32_e32 v49, 0, v49
	global_store_dwordx4 v[60:61], v[56:59], off
	s_nop 1
	v_pk_mul_f32 v[56:57], v[48:49], v[48:49]
	v_max_f32_e32 v50, 0, v50
	v_max_f32_e32 v52, 0, v52
	v_max_f32_e32 v53, 0, v53
	v_max_f32_e32 v48, 0, v54
	v_max_f32_e32 v49, 0, v55
	v_max_f32_e32 v51, 0, v51
	v_pk_mul_f32 v[52:53], v[52:53], v[52:53]
	v_pk_mul_f32 v[54:55], v[48:49], v[48:49]
	v_pk_mul_f32 v[58:59], v[50:51], v[50:51]
	v_cvt_pk_bf16_f32 v48, v52, v53
	v_cvt_pk_bf16_f32 v49, v54, v55
	v_cvt_pk_bf16_f32 v50, v56, v57
	v_cvt_pk_bf16_f32 v51, v58, v59
	v_max_f32_e32 v40, 0, v40
	v_max_f32_e32 v41, 0, v41
	global_store_dwordx4 v[64:65], v[48:51], off offset:256
	s_nop 1
	v_pk_mul_f32 v[50:51], v[40:41], v[40:41]
	s_mov_b64 s[4:5], 0x120000
	v_max_f32_e32 v44, 0, v44
	v_max_f32_e32 v45, 0, v45
	v_max_f32_e32 v42, 0, v42
	v_lshl_add_u64 v[48:49], v[138:139], 0, s[4:5]
	v_pk_mul_f32 v[44:45], v[44:45], v[44:45]
	v_max_f32_e32 v40, 0, v46
	v_max_f32_e32 v41, 0, v47
	v_max_f32_e32 v43, 0, v43
	s_mov_b32 s4, 0x120000
	v_pk_mul_f32 v[46:47], v[40:41], v[40:41]
	v_pk_mul_f32 v[52:53], v[42:43], v[42:43]
	v_cvt_pk_bf16_f32 v40, v44, v45
	v_add_co_u32_e32 v44, vcc, s4, v138
	v_cvt_pk_bf16_f32 v41, v46, v47
	v_cvt_pk_bf16_f32 v42, v50, v51
	v_cvt_pk_bf16_f32 v43, v52, v53
	v_addc_co_u32_e32 v45, vcc, 0, v139, vcc
	v_max_f32_e32 v32, 0, v32
	v_max_f32_e32 v33, 0, v33
	global_store_dwordx4 v[44:45], v[40:43], off
	s_nop 1
	v_pk_mul_f32 v[40:41], v[32:33], v[32:33]
	v_max_f32_e32 v34, 0, v34
	v_max_f32_e32 v36, 0, v36
	v_max_f32_e32 v37, 0, v37
	v_max_f32_e32 v32, 0, v38
	v_max_f32_e32 v33, 0, v39
	v_max_f32_e32 v35, 0, v35
	v_pk_mul_f32 v[36:37], v[36:37], v[36:37]
	v_pk_mul_f32 v[38:39], v[32:33], v[32:33]
	v_pk_mul_f32 v[42:43], v[34:35], v[34:35]
	v_cvt_pk_bf16_f32 v32, v36, v37
	v_cvt_pk_bf16_f32 v33, v38, v39
	v_cvt_pk_bf16_f32 v34, v40, v41
	v_cvt_pk_bf16_f32 v35, v42, v43
	v_max_f32_e32 v24, 0, v24
	v_max_f32_e32 v25, 0, v25
	global_store_dwordx4 v[48:49], v[32:35], off offset:256
	s_nop 1
	v_pk_mul_f32 v[34:35], v[24:25], v[24:25]
	s_mov_b64 s[4:5], 0x140000
	v_max_f32_e32 v28, 0, v28
	v_max_f32_e32 v29, 0, v29
	v_max_f32_e32 v26, 0, v26
	v_lshl_add_u64 v[32:33], v[138:139], 0, s[4:5]
	v_pk_mul_f32 v[28:29], v[28:29], v[28:29]
	v_max_f32_e32 v24, 0, v30
	v_max_f32_e32 v25, 0, v31
	v_max_f32_e32 v27, 0, v27
	s_mov_b32 s4, 0x140000
	v_pk_mul_f32 v[30:31], v[24:25], v[24:25]
	v_pk_mul_f32 v[36:37], v[26:27], v[26:27]
	v_cvt_pk_bf16_f32 v24, v28, v29
	v_add_co_u32_e32 v28, vcc, s4, v138
	v_cvt_pk_bf16_f32 v25, v30, v31
	v_cvt_pk_bf16_f32 v26, v34, v35
	v_cvt_pk_bf16_f32 v27, v36, v37
	v_addc_co_u32_e32 v29, vcc, 0, v139, vcc
	v_max_f32_e32 v16, 0, v16
	v_max_f32_e32 v17, 0, v17
	global_store_dwordx4 v[28:29], v[24:27], off
	s_nop 1
	v_pk_mul_f32 v[24:25], v[16:17], v[16:17]
	v_max_f32_e32 v18, 0, v18
	v_max_f32_e32 v20, 0, v20
	v_max_f32_e32 v21, 0, v21
	v_max_f32_e32 v16, 0, v22
	v_max_f32_e32 v17, 0, v23
	v_max_f32_e32 v19, 0, v19
	v_pk_mul_f32 v[20:21], v[20:21], v[20:21]
	v_pk_mul_f32 v[22:23], v[16:17], v[16:17]
	v_pk_mul_f32 v[26:27], v[18:19], v[18:19]
	v_cvt_pk_bf16_f32 v16, v20, v21
	v_cvt_pk_bf16_f32 v17, v22, v23
	v_cvt_pk_bf16_f32 v18, v24, v25
	v_cvt_pk_bf16_f32 v19, v26, v27
	v_max_f32_e32 v8, 0, v8
	v_max_f32_e32 v9, 0, v9
	global_store_dwordx4 v[32:33], v[16:19], off offset:256
	s_nop 1
	v_pk_mul_f32 v[18:19], v[8:9], v[8:9]
	s_mov_b64 s[4:5], 0x160000
	v_max_f32_e32 v12, 0, v12
	v_max_f32_e32 v13, 0, v13
	v_max_f32_e32 v10, 0, v10
	v_lshl_add_u64 v[16:17], v[138:139], 0, s[4:5]
	v_pk_mul_f32 v[12:13], v[12:13], v[12:13]
	v_max_f32_e32 v8, 0, v14
	v_max_f32_e32 v9, 0, v15
	v_max_f32_e32 v11, 0, v11
	s_mov_b32 s4, 0x160000
	v_pk_mul_f32 v[14:15], v[8:9], v[8:9]
	v_pk_mul_f32 v[20:21], v[10:11], v[10:11]
	v_cvt_pk_bf16_f32 v8, v12, v13
	v_add_co_u32_e32 v12, vcc, s4, v138
	v_cvt_pk_bf16_f32 v9, v14, v15
	v_cvt_pk_bf16_f32 v10, v18, v19
	v_cvt_pk_bf16_f32 v11, v20, v21
	v_addc_co_u32_e32 v13, vcc, 0, v139, vcc
	v_max_f32_e32 v0, 0, v0
	v_max_f32_e32 v1, 0, v1
	global_store_dwordx4 v[12:13], v[8:11], off
	s_nop 1
	v_pk_mul_f32 v[8:9], v[0:1], v[0:1]
	v_max_f32_e32 v2, 0, v2
	v_max_f32_e32 v4, 0, v4
	v_max_f32_e32 v5, 0, v5
	v_max_f32_e32 v0, 0, v6
	v_max_f32_e32 v1, 0, v7
	v_max_f32_e32 v3, 0, v3
	v_pk_mul_f32 v[4:5], v[4:5], v[4:5]
	v_pk_mul_f32 v[6:7], v[0:1], v[0:1]
	v_pk_mul_f32 v[10:11], v[2:3], v[2:3]
	v_cvt_pk_bf16_f32 v0, v4, v5
	v_cvt_pk_bf16_f32 v1, v6, v7
	v_cvt_pk_bf16_f32 v2, v8, v9
	v_cvt_pk_bf16_f32 v3, v10, v11
	s_andn2_b64 vcc, exec, s[8:9]
	s_mov_b64 s[4:5], -1
	global_store_dwordx4 v[16:17], v[0:3], off offset:256
	s_cbranch_vccnz .LBB0_281
	s_andn2_b64 vcc, exec, s[10:11]
	s_cbranch_vccnz .LBB0_280
	s_barrier
	s_branch .LBB0_280
